# window loop also runs at s_setprio 1 (all compute at raised priority, bookkeeping/epilogues at 0)
# speedup vs baseline: 1.0049x; 1.0027x over previous
.LBB0_669:
	s_waitcnt lgkmcnt(0)
	v_mov_b32_e32 v162, 0
	s_cmp_lt_i32 s29, 0
	v_mov_b32_e32 v158, 0
	v_mov_b32_e32 v154, 0
	v_mov_b32_e32 v150, 0
	v_mov_b32_e32 v149, v162
	v_mov_b32_e32 v148, v162
	v_mov_b32_e32 v147, v162
	v_mov_b32_e32 v146, v162
	v_mov_b32_e32 v133, v162
	v_mov_b32_e32 v132, v162
	v_mov_b32_e32 v131, v162
	v_mov_b32_e32 v130, v162
	v_mov_b32_e32 v99, v162
	v_mov_b32_e32 v98, v162
	v_mov_b32_e32 v97, v162
	v_mov_b32_e32 v96, v162
	v_mov_b32_e32 v83, v162
	v_mov_b32_e32 v82, v162
	v_mov_b32_e32 v81, v162
	v_mov_b32_e32 v80, v162
	v_mov_b32_e32 v145, v162
	v_mov_b32_e32 v144, v162
	v_mov_b32_e32 v143, v162
	v_mov_b32_e32 v142, v162
	v_mov_b32_e32 v127, v162
	v_mov_b32_e32 v126, v162
	v_mov_b32_e32 v125, v162
	v_mov_b32_e32 v124, v162
	v_mov_b32_e32 v95, v162
	v_mov_b32_e32 v94, v162
	v_mov_b32_e32 v93, v162
	v_mov_b32_e32 v92, v162
	v_mov_b32_e32 v79, v162
	v_mov_b32_e32 v78, v162
	v_mov_b32_e32 v77, v162
	v_mov_b32_e32 v76, v162
	v_mov_b32_e32 v141, v162
	v_mov_b32_e32 v140, v162
	v_mov_b32_e32 v139, v162
	v_mov_b32_e32 v138, v162
	v_mov_b32_e32 v123, v162
	v_mov_b32_e32 v122, v162
	v_mov_b32_e32 v121, v162
	v_mov_b32_e32 v120, v162
	v_mov_b32_e32 v91, v162
	v_mov_b32_e32 v90, v162
	v_mov_b32_e32 v89, v162
	v_mov_b32_e32 v88, v162
	v_mov_b32_e32 v71, v162
	v_mov_b32_e32 v70, v162
	v_mov_b32_e32 v69, v162
	v_mov_b32_e32 v68, v162
	v_mov_b32_e32 v137, v162
	v_mov_b32_e32 v136, v162
	v_mov_b32_e32 v135, v162
	v_mov_b32_e32 v134, v162
	v_mov_b32_e32 v119, v162
	v_mov_b32_e32 v118, v162
	v_mov_b32_e32 v117, v162
	v_mov_b32_e32 v116, v162
	v_mov_b32_e32 v87, v162
	v_mov_b32_e32 v86, v162
	v_mov_b32_e32 v85, v162
	v_mov_b32_e32 v84, v162
	v_mov_b32_e32 v35, v162
	v_mov_b32_e32 v34, v162
	v_mov_b32_e32 v33, v162
	v_mov_b32_e32 v32, v162
	s_barrier
	s_cbranch_scc1 .LBB0_748
	v_and_b32_e32 v35, 12, v73
	s_movk_i32 s2, 0x1320
	v_lshrrev_b32_e32 v32, 4, v73
	v_lshrrev_b32_e64 v35, v35, s2
	v_xor_b32_e32 v32, v35, v32
	v_lshlrev_b32_e32 v34, 6, v101
	v_lshlrev_b32_e32 v32, 4, v32
	v_and_or_b32 v217, v32, 48, v34
	v_lshrrev_b32_e32 v32, 1, v101
	s_lshl_b32 s70, s40, 6
	s_lshl_b32 s2, s64, 6
	v_xor_b32_e32 v34, v32, v100
	v_bitop3_b32 v32, v100, v32, 4 bitop3:0x36
	s_add_i32 s2, s70, s2
	v_lshlrev_b32_e32 v35, 4, v32
	v_lshrrev_b32_e32 v32, 2, v101
	v_lshl_or_b32 v68, v100, 2, s2
	v_sub_u32_e32 v32, v68, v32
	v_lshlrev_b32_e32 v33, 7, v101
	v_lshlrev_b32_e32 v34, 4, v34
	v_sub_u32_e32 v242, v32, v240
	v_mov_b32_e32 v32, 0
	v_mov_b32_e32 v73, v72
	v_mov_b32_e32 v74, v72
	v_mov_b32_e32 v75, v72
	s_add_i32 s65, s41, 0xfffffe0f
	s_mov_b32 s71, 0
	v_add_u32_e32 v243, v33, v34
	v_add_u32_e32 v244, v33, v35
	s_mov_b32 s74, 0
	v_mov_b32_e32 v33, v32
	v_mov_b32_e32 v34, v32
	v_mov_b32_e32 v35, v32
	v_mov_b32_e32 v68, v32
	v_mov_b32_e32 v69, v32
	v_mov_b32_e32 v70, v32
	v_mov_b32_e32 v71, v32
	v_mov_b32_e32 v76, v32
	v_mov_b32_e32 v77, v32
	v_mov_b32_e32 v78, v32
	v_mov_b32_e32 v79, v32
	v_mov_b32_e32 v80, v32
	v_mov_b32_e32 v81, v32
	v_mov_b32_e32 v82, v32
	v_mov_b32_e32 v83, v32
	v_mov_b32_e32 v84, v32
	v_mov_b32_e32 v85, v32
	v_mov_b32_e32 v86, v32
	v_mov_b32_e32 v87, v32
	v_mov_b32_e32 v88, v32
	v_mov_b32_e32 v89, v32
	v_mov_b32_e32 v90, v32
	v_mov_b32_e32 v91, v32
	v_mov_b32_e32 v92, v32
	v_mov_b32_e32 v93, v32
	v_mov_b32_e32 v94, v32
	v_mov_b32_e32 v95, v32
	v_mov_b32_e32 v96, v32
	v_mov_b32_e32 v97, v32
	v_mov_b32_e32 v98, v32
	v_mov_b32_e32 v99, v32
	v_mov_b32_e32 v116, v32
	v_mov_b32_e32 v117, v32
	v_mov_b32_e32 v118, v32
	v_mov_b32_e32 v119, v32
	v_mov_b32_e32 v120, v32
	v_mov_b32_e32 v121, v32
	v_mov_b32_e32 v122, v32
	v_mov_b32_e32 v123, v32
	v_mov_b32_e32 v124, v32
	v_mov_b32_e32 v125, v32
	v_mov_b32_e32 v126, v32
	v_mov_b32_e32 v127, v32
	v_mov_b32_e32 v130, v32
	v_mov_b32_e32 v131, v32
	v_mov_b32_e32 v132, v32
	v_mov_b32_e32 v133, v32
	v_mov_b32_e32 v134, v32
	v_mov_b32_e32 v135, v32
	v_mov_b32_e32 v136, v32
	v_mov_b32_e32 v137, v32
	v_mov_b32_e32 v138, v32
	v_mov_b32_e32 v139, v32
	v_mov_b32_e32 v140, v32
	v_mov_b32_e32 v141, v32
	v_mov_b32_e32 v142, v32
	v_mov_b32_e32 v143, v32
	v_mov_b32_e32 v144, v32
	v_mov_b32_e32 v145, v32
	v_mov_b32_e32 v146, v32
	v_mov_b32_e32 v147, v32
	v_mov_b32_e32 v148, v32
	v_mov_b32_e32 v149, v32
	v_mov_b32_e32 v150, v32
	v_mov_b32_e32 v151, v32
	v_mov_b32_e32 v152, v32
	v_mov_b32_e32 v153, v32
	v_mov_b32_e32 v154, v32
	v_mov_b32_e32 v155, v32
	v_mov_b32_e32 v156, v32
	v_mov_b32_e32 v157, v32
	v_mov_b32_e32 v158, v32
	v_mov_b32_e32 v159, v32
	v_mov_b32_e32 v160, v32
	v_mov_b32_e32 v161, v32
	v_mov_b32_e32 v162, v32
	v_mov_b32_e32 v163, v32
	v_mov_b32_e32 v164, v32
	v_mov_b32_e32 v165, v32
	s_setprio 1
	s_cmp_lt_i32 s74, s29
	s_cselect_b64 s[46:47], -1, 0
	s_cmp_ge_i32 s74, s29
	s_cbranch_scc0 .LBB0_672
	s_branch .LBB0_673

.LBB0_748:
	s_setprio 0
	s_waitcnt vmcnt(3)
	v_mul_u32_u24_e32 v0, 3, v214
	v_lshlrev_b32_e32 v0, 2, v0
	v_mov_b32_e32 v1, v129
	v_lshl_add_u64 v[2:3], s[58:59], 0, v[0:1]
	s_waitcnt vmcnt(1)
	v_lshlrev_b64 v[8:9], 7, v[200:201]
	v_lshl_add_u64 v[210:211], v[2:3], 0, v[8:9]
	global_load_dword v14, v[210:211], off offset:40
	v_add_f32_e32 v4, 0, v162
	v_lshlrev_b32_e32 v0, 2, v203
	v_lshl_add_u64 v[0:1], s[60:61], 0, v[0:1]
	v_mov_b32_e32 v203, v129
	v_lshl_add_u64 v[0:1], v[0:1], 0, v[202:203]
	v_lshlrev_b64 v[214:215], 11, v[200:201]
	v_lshl_add_u64 v[202:203], v[0:1], 0, v[214:215]
	global_load_dwordx4 v[56:59], v[202:203], off
	global_load_dwordx4 v[104:107], v[202:203], off offset:64
	global_load_dwordx4 v[108:111], v[202:203], off offset:128
	global_load_dwordx4 v[112:115], v[202:203], off offset:192
	v_add_f32_e32 v5, 0, v150
	v_add_f32_e32 v7, 0, v158
	v_lshlrev_b64 v[216:217], 11, v[204:205]
	v_lshl_add_u64 v[192:193], v[0:1], 0, v[216:217]
	global_load_dwordx4 v[174:177], v[192:193], off
	global_load_dwordx4 v[178:181], v[192:193], off offset:64
	global_load_dwordx4 v[182:185], v[192:193], off offset:128
	global_load_dwordx4 v[186:189], v[192:193], off offset:192
	v_add_f32_e32 v6, 0, v154
	s_lshl_b32 s29, s45, 6
	s_lshl_b32 s28, s28, 20
	s_waitcnt vmcnt(8)
	v_mul_f32_e32 v8, 0xbfb8aa3b, v14
	v_exp_f32_e32 v8, v8
	s_nop 0
	v_add_f32_e32 v8, 1.0, v8
	v_rcp_f32_e32 v8, v8
	s_nop 0
	v_div_scale_f32 v9, s[2:3], v4, v4, v8
	v_rcp_f32_e32 v10, v9
	s_nop 0
	v_fma_f32 v11, -v9, v10, 1.0
	v_fmac_f32_e32 v10, v11, v10
	v_div_scale_f32 v11, vcc, v8, v4, v8
	v_mul_f32_e32 v12, v11, v10
	v_fma_f32 v13, -v9, v12, v11
	v_fmac_f32_e32 v12, v13, v10
	v_fma_f32 v9, -v9, v12, v11
	v_div_fmas_f32 v9, v9, v10, v12
	v_div_fixup_f32 v4, v9, v4, v8
	v_mov_b32_e32 v13, v129
	s_waitcnt vmcnt(7)
	v_pk_fma_f32 v[8:9], v[146:147], v[4:5], v[56:57] op_sel_hi:[1,0,1]
	v_pk_fma_f32 v[10:11], v[148:149], v[4:5], v[58:59] op_sel_hi:[1,0,1]
	global_store_dwordx4 v[202:203], v[8:11], off
	s_nop 1
	s_waitcnt vmcnt(7)
	v_pk_fma_f32 v[8:9], v[142:143], v[4:5], v[104:105] op_sel_hi:[1,0,1]
	v_pk_fma_f32 v[10:11], v[144:145], v[4:5], v[106:107] op_sel_hi:[1,0,1]
	global_store_dwordx4 v[202:203], v[8:11], off offset:64
	s_nop 1
	s_waitcnt vmcnt(7)
	v_pk_fma_f32 v[8:9], v[138:139], v[4:5], v[108:109] op_sel_hi:[1,0,1]
	v_pk_fma_f32 v[10:11], v[140:141], v[4:5], v[110:111] op_sel_hi:[1,0,1]
	global_store_dwordx4 v[202:203], v[8:11], off offset:128
	s_nop 1
	s_waitcnt vmcnt(7)
	v_pk_fma_f32 v[8:9], v[134:135], v[4:5], v[112:113] op_sel_hi:[1,0,1]
	v_pk_fma_f32 v[10:11], v[136:137], v[4:5], v[114:115] op_sel_hi:[1,0,1]
	global_store_dwordx4 v[202:203], v[8:11], off offset:192
	s_nop 1
	s_nop 1
	v_lshlrev_b64 v[8:9], 7, v[204:205]
	v_lshl_add_u64 v[212:213], v[2:3], 0, v[8:9]
	global_load_dword v15, v[212:213], off offset:40
	v_lshlrev_b64 v[204:205], 11, v[206:207]
	v_lshl_add_u64 v[194:195], v[0:1], 0, v[204:205]
	global_load_dwordx4 v[242:245], v[194:195], off
	global_load_dwordx4 v[246:249], v[194:195], off offset:64
	global_load_dwordx4 v[56:59], v[194:195], off offset:128
	global_load_dwordx4 v[104:107], v[194:195], off offset:192
	s_waitcnt vmcnt(4)
	v_mul_f32_e32 v4, 0xbfb8aa3b, v15
	v_exp_f32_e32 v4, v4
	s_nop 0
	v_add_f32_e32 v4, 1.0, v4
	v_rcp_f32_e32 v4, v4
	s_nop 0
	v_div_scale_f32 v8, s[2:3], v7, v7, v4
	v_rcp_f32_e32 v9, v8
	s_nop 0
	v_fma_f32 v10, -v8, v9, 1.0
	v_fmac_f32_e32 v9, v10, v9
	v_div_scale_f32 v10, vcc, v4, v7, v4
	v_mul_f32_e32 v11, v10, v9
	v_fma_f32 v12, -v8, v11, v10
	v_fmac_f32_e32 v11, v12, v9
	v_fma_f32 v8, -v8, v11, v10
	v_div_fmas_f32 v8, v8, v9, v11
	v_div_fixup_f32 v4, v8, v7, v4
	v_pk_fma_f32 v[8:9], v[130:131], v[4:5], v[174:175] op_sel_hi:[1,0,1]
	v_pk_fma_f32 v[10:11], v[132:133], v[4:5], v[176:177] op_sel_hi:[1,0,1]
	global_store_dwordx4 v[192:193], v[8:11], off
	s_nop 1
	v_pk_fma_f32 v[8:9], v[124:125], v[4:5], v[178:179] op_sel_hi:[1,0,1]
	v_pk_fma_f32 v[10:11], v[126:127], v[4:5], v[180:181] op_sel_hi:[1,0,1]
	global_store_dwordx4 v[192:193], v[8:11], off offset:64
	s_nop 1
	v_pk_fma_f32 v[8:9], v[120:121], v[4:5], v[182:183] op_sel_hi:[1,0,1]
	v_pk_fma_f32 v[10:11], v[122:123], v[4:5], v[184:185] op_sel_hi:[1,0,1]
	global_store_dwordx4 v[192:193], v[8:11], off offset:128
	s_nop 1
	v_pk_fma_f32 v[8:9], v[116:117], v[4:5], v[186:187] op_sel_hi:[1,0,1]
	v_pk_fma_f32 v[10:11], v[118:119], v[4:5], v[188:189] op_sel_hi:[1,0,1]
	global_store_dwordx4 v[192:193], v[8:11], off offset:192
	s_nop 1
	s_nop 1
	v_lshlrev_b64 v[8:9], 7, v[206:207]
	v_lshl_add_u64 v[196:197], v[2:3], 0, v[8:9]
	global_load_dword v151, v[196:197], off offset:40
	v_lshlrev_b64 v[206:207], 11, v[208:209]
	v_lshl_add_u64 v[190:191], v[0:1], 0, v[206:207]
	global_load_dwordx4 v[108:111], v[190:191], off
	global_load_dwordx4 v[112:115], v[190:191], off offset:64
	global_load_dwordx4 v[174:177], v[190:191], off offset:128
	global_load_dwordx4 v[178:181], v[190:191], off offset:192
	s_waitcnt vmcnt(4)
	v_mul_f32_e32 v4, 0xbfb8aa3b, v151
	v_exp_f32_e32 v4, v4
	s_nop 0
	v_add_f32_e32 v4, 1.0, v4
	v_rcp_f32_e32 v4, v4
	s_nop 0
	v_div_scale_f32 v7, s[2:3], v6, v6, v4
	v_rcp_f32_e32 v8, v7
	s_nop 0
	v_fma_f32 v9, -v7, v8, 1.0
	v_fmac_f32_e32 v8, v9, v8
	v_div_scale_f32 v9, vcc, v4, v6, v4
	v_mul_f32_e32 v10, v9, v8
	v_fma_f32 v11, -v7, v10, v9
	v_fmac_f32_e32 v10, v11, v8
	v_fma_f32 v7, -v7, v10, v9
	v_div_fmas_f32 v7, v7, v8, v10
	v_div_fixup_f32 v4, v7, v6, v4
	v_pk_fma_f32 v[6:7], v[96:97], v[4:5], v[242:243] op_sel_hi:[1,0,1]
	v_pk_fma_f32 v[8:9], v[98:99], v[4:5], v[244:245] op_sel_hi:[1,0,1]
	global_store_dwordx4 v[194:195], v[6:9], off
	s_nop 1
	v_pk_fma_f32 v[6:7], v[92:93], v[4:5], v[246:247] op_sel_hi:[1,0,1]
	v_pk_fma_f32 v[8:9], v[94:95], v[4:5], v[248:249] op_sel_hi:[1,0,1]
	global_store_dwordx4 v[194:195], v[6:9], off offset:64
	s_nop 1
	v_pk_fma_f32 v[6:7], v[88:89], v[4:5], v[56:57] op_sel_hi:[1,0,1]
	v_pk_fma_f32 v[8:9], v[90:91], v[4:5], v[58:59] op_sel_hi:[1,0,1]
	global_store_dwordx4 v[194:195], v[6:9], off offset:128
	s_nop 1
	v_pk_fma_f32 v[6:7], v[84:85], v[4:5], v[104:105] op_sel_hi:[1,0,1]
	v_pk_fma_f32 v[8:9], v[86:87], v[4:5], v[106:107] op_sel_hi:[1,0,1]
	global_store_dwordx4 v[194:195], v[6:9], off offset:192
	s_nop 1
	s_nop 1
	v_lshlrev_b64 v[6:7], 7, v[208:209]
	v_lshl_add_u64 v[200:201], v[2:3], 0, v[6:7]
	global_load_dword v152, v[200:201], off offset:40
	s_waitcnt vmcnt(0)
	v_mul_f32_e32 v2, 0xbfb8aa3b, v152
	v_exp_f32_e32 v2, v2
	s_nop 0
	v_add_f32_e32 v2, 1.0, v2
	v_rcp_f32_e32 v2, v2
	s_nop 0
	v_div_scale_f32 v3, s[2:3], v5, v5, v2
	v_rcp_f32_e32 v4, v3
	s_lshl_b32 s2, s29, 1
	s_add_u32 s2, s26, s2
	s_addc_u32 s3, s27, 0
	v_fma_f32 v6, -v3, v4, 1.0
	v_fmac_f32_e32 v4, v6, v4
	v_div_scale_f32 v6, vcc, v2, v5, v2
	v_mul_f32_e32 v7, v6, v4
	v_fma_f32 v8, -v3, v7, v6
	v_fmac_f32_e32 v7, v8, v4
	v_fma_f32 v3, -v3, v7, v6
	v_div_fmas_f32 v3, v3, v4, v7
	v_div_fixup_f32 v2, v3, v5, v2
	v_mov_b32_e32 v8, v218
	s_lshl_b32 s26, s28, 1
	s_add_u32 s26, s67, s26
	s_addc_u32 s27, s68, 0
	s_cmpk_eq_i32 s64, 0xff
	v_pk_fma_f32 v[4:5], v[80:81], v[2:3], v[108:109] op_sel_hi:[1,0,1]
	v_pk_fma_f32 v[6:7], v[82:83], v[2:3], v[110:111] op_sel_hi:[1,0,1]
	global_store_dwordx4 v[190:191], v[4:7], off
	s_nop 1
	v_pk_fma_f32 v[4:5], v[76:77], v[2:3], v[112:113] op_sel_hi:[1,0,1]
	v_pk_fma_f32 v[6:7], v[78:79], v[2:3], v[114:115] op_sel_hi:[1,0,1]
	global_store_dwordx4 v[190:191], v[4:7], off offset:64
	s_nop 1
	v_pk_fma_f32 v[4:5], v[68:69], v[2:3], v[174:175] op_sel_hi:[1,0,1]
	v_pk_fma_f32 v[6:7], v[70:71], v[2:3], v[176:177] op_sel_hi:[1,0,1]
	global_store_dwordx4 v[190:191], v[4:7], off offset:128
	s_nop 1
	v_pk_fma_f32 v[0:1], v[32:33], v[2:3], v[178:179] op_sel_hi:[1,0,1]
	v_pk_fma_f32 v[2:3], v[34:35], v[2:3], v[180:181] op_sel_hi:[1,0,1]
	global_store_dwordx4 v[190:191], v[0:3], off offset:192
	s_nop 1
	s_nop 0
	v_ashrrev_i32_e32 v9, 3, v8
	v_mov_b64_e32 v[0:1], s[2:3]
	v_lshlrev_b32_e32 v10, 4, v8
	v_ashrrev_i32_e32 v6, 2, v8
	v_mad_i64_i32 v[0:1], s[2:3], v9, s10, v[0:1]
	v_and_b32_e32 v2, 0x70, v10
	v_mov_b32_e32 v3, v129
	v_ashrrev_i32_e32 v7, 31, v6
	v_lshl_add_u64 v[208:209], v[0:1], 0, v[2:3]
	v_lshlrev_b64 v[0:1], 7, v[6:7]
	v_lshl_add_u64 v[4:5], s[26:27], 0, v[0:1]
	v_and_b32_e32 v12, 48, v10
	v_lshl_add_u64 v[4:5], v[4:5], 0, v[12:13]
	v_add_co_u32_e32 v12, vcc, 0x30000, v208
	s_waitcnt lgkmcnt(2)
	global_load_dwordx4 v[56:59], v[208:209], off offset:3584
	v_addc_co_u32_e32 v13, vcc, 0, v209, vcc
	global_load_dwordx4 v[68:71], v[12:13], off offset:3584
	global_load_dwordx4 v[84:87], v[4:5], off
	global_load_dwordx4 v[96:99], v[4:5], off offset:64
	s_mov_b64 s[2:3], 0xe00
	v_lshl_add_u64 v[2:3], v[208:209], 0, s[2:3]
	s_cbranch_scc1 .LBB0_750
	v_add_co_u32_e32 v12, vcc, 0x60000, v2
	s_nop 1
	v_addc_co_u32_e32 v13, vcc, 0, v3, vcc
	v_add_co_u32_e32 v14, vcc, 0x90000, v2
	s_nop 1
	v_addc_co_u32_e32 v15, vcc, 0, v3, vcc
	global_load_dwordx4 v[76:79], v[12:13], off
	global_load_dwordx4 v[80:83], v[14:15], off
	v_add_co_u32_e32 v12, vcc, 0x2000, v4
	s_nop 1
	v_addc_co_u32_e32 v13, vcc, 0, v5, vcc
	global_load_dwordx4 v[88:91], v[12:13], off
	global_load_dwordx4 v[92:95], v[12:13], off offset:64
